# pair8f plus one s_barrier per row in the P3 merge loop and the P6 LayerNorm loop (the eight waves of a CU stream neighbouring rows in step)
# speedup vs baseline: 1.0057x; 1.0029x over previous
;     __device__ __forceinline__ unsigned a(const pg8::Unit& u) const { return (unsigned)u.pm * (256u * K * 2u); }
;     __device__ __forceinline__ unsigned a(const pg8::Unit& u) const { return (unsigned)u.pm * (256u * K * 2u); }
;     __device__ __forceinline__ unsigned a(const pg8::Unit& u) const { return (unsigned)u.pm * (256u * K * 2u); }
;     __device__ __forceinline__ unsigned a(const pg8::Unit& u) const { return (unsigned)u.pm * (256u * K * 2u); }
;     __device__ __forceinline__ unsigned a(const pg8::Unit& u) const { return (unsigned)u.pm * (256u * K * 2u); }
; __device__ __forceinline__ void p3_combine(const Frame& F) {
;     ...
;     for (int m = gw; m < M; m += NGW) {
; #pragma unroll
;         for (int j = 0; j < 4; ++j) {
;             const int col = j * 512 + lane * 8, head = col >> 7; const size_t e = (size_t)m * EB + col;
;             const int sq = m >> 13, pos = m & (SEQ - 1);
;             const float l0 = F.LSE[((size_t)(0 * 16 + head) * NSEQ + sq) * SEQ + pos], l1 = F.LSE[((size_t)(1 * 16 + head) * NSEQ + sq) * SEQ + ((pos & 3) << 11) + (pos >> 2)],
;                         l2 = F.LSE[((size_t)(2 * 16 + head) * NSEQ + sq) * SEQ + ((pos & 15) << 9) + (pos >> 4)];
;             const float mx = fmaxf(l0, fmaxf(l1, l2));
;             float e0 = __builtin_amdgcn_exp2f(l0 - mx), e1 = __builtin_amdgcn_exp2f(l1 - mx), e2 = __builtin_amdgcn_exp2f(l2 - mx);
;             const float inv = 1.f / (e0 + e1 + e2); e0 *= inv; e1 *= inv; e2 *= inv;
;             const u32x2 a = *(const u32x2*)((const unsigned char*)F.OG0 + e), b = *(const u32x2*)((const unsigned char*)F.OG1 + e), c = *(const u32x2*)((const unsigned char*)F.OG2 + e);
;             const u32x4 z = *(const u32x4*)(F.ZB + e);
;             const unsigned aw[2] = {a.x, a.y}, bw[2] = {b.x, b.y}, cw[2] = {c.x, c.y}, zw[4] = {z.x, z.y, z.z, z.w};
.LBB0_365:
	s_barrier
	v_lshl_add_u64 v[36:37], s[18:19], 0, v[4:5]
	v_add_co_u32_e32 v44, vcc, s7, v36
	s_ashr_i32 s64, s6, 13
	s_nop 0
	v_addc_co_u32_e32 v45, vcc, 0, v37, vcc
	v_add_co_u32_e32 v46, vcc, s9, v36
	v_lshl_add_u64 v[42:43], s[24:25], 0, v[4:5]
	s_nop 0
	v_addc_co_u32_e32 v47, vcc, 0, v37, vcc
	v_add_co_u32_e32 v48, vcc, s11, v36
	s_ashr_i32 s65, s64, 31
	s_nop 0
	v_addc_co_u32_e32 v49, vcc, 0, v37, vcc
	v_add_co_u32_e32 v36, vcc, s33, v42
	global_load_dwordx4 v[0:3], v[30:31], off offset:-3072
	s_nop 0
	v_addc_co_u32_e32 v37, vcc, 0, v43, vcc
	v_lshl_add_u64 v[42:43], s[64:65], 0, v[6:7]
	v_lshl_add_u64 v[50:51], s[64:65], 0, v[8:9]
	v_lshl_add_u64 v[52:53], s[64:65], 0, v[10:11]
	s_and_b32 s35, s6, 0x1fff
	s_and_b32 s58, s3, 0x1800
	s_and_b32 s62, s0, 0x1e00
	global_load_dwordx2 v[54:55], v[44:45], off
	global_load_dwordx2 v[56:57], v[46:47], off
	global_load_dwordx2 v[58:59], v[48:49], off
	v_lshl_add_u64 v[72:73], s[64:65], 0, v[24:25]
	v_lshl_add_u64 v[74:75], s[64:65], 0, v[26:27]
	v_lshl_add_u64 v[76:77], s[64:65], 0, v[28:29]
	v_lshlrev_b64 v[42:43], 15, v[42:43]
	v_lshlrev_b64 v[50:51], 15, v[50:51]
	v_lshlrev_b64 v[52:53], 15, v[52:53]
	s_lshr_b32 s60, s6, 2
	s_mov_b32 s57, s51
	s_mov_b32 s59, s51
	s_mov_b32 s63, s51
	s_lshl_b32 s56, s35, 2
	s_lshl_b32 s58, s58, 2
	s_lshl_b32 s62, s62, 2
	v_lshlrev_b64 v[72:73], 15, v[72:73]
	v_lshlrev_b64 v[74:75], 15, v[74:75]
	v_lshlrev_b64 v[76:77], 15, v[76:77]
	v_lshl_add_u64 v[42:43], s[54:55], 0, v[42:43]
	v_lshl_add_u64 v[50:51], s[54:55], 0, v[50:51]
	v_lshl_add_u64 v[52:53], s[54:55], 0, v[52:53]
	s_and_b32 s50, s6, 0x1ffc
	s_mov_b32 s61, s51
	s_and_b32 s60, s60, 0x7fc
	v_lshl_add_u64 v[72:73], s[54:55], 0, v[72:73]
	v_lshl_add_u64 v[74:75], s[54:55], 0, v[74:75]
	v_lshl_add_u64 v[76:77], s[54:55], 0, v[76:77]
	v_lshl_add_u64 v[78:79], v[42:43], 0, s[56:57]
	v_lshl_add_u64 v[50:51], v[50:51], 0, s[58:59]
	v_lshl_add_u64 v[52:53], v[52:53], 0, s[62:63]
	v_lshl_add_u64 v[42:43], v[72:73], 0, s[56:57]
	v_lshl_add_u64 v[72:73], v[74:75], 0, s[58:59]
	v_lshl_add_u64 v[74:75], v[76:77], 0, s[62:63]
	v_lshl_add_u64 v[76:77], v[50:51], 0, s[50:51]
	v_lshl_add_u64 v[80:81], v[52:53], 0, s[60:61]
	global_load_dword v87, v[78:79], off
	global_load_dword v90, v[76:77], off
	global_load_dword v91, v[80:81], off
	v_lshl_add_u64 v[52:53], v[74:75], 0, s[60:61]
	v_lshl_add_u64 v[50:51], v[72:73], 0, s[50:51]
	v_lshl_add_u64 v[60:61], s[64:65], 0, v[12:13]
	v_lshl_add_u64 v[66:67], s[64:65], 0, v[18:19]
	v_lshlrev_b64 v[60:61], 15, v[60:61]
	v_lshlrev_b64 v[66:67], 15, v[66:67]
	v_lshl_add_u64 v[60:61], s[54:55], 0, v[60:61]
	v_lshl_add_u64 v[66:67], s[54:55], 0, v[66:67]
	v_lshl_add_u64 v[60:61], v[60:61], 0, s[56:57]
	v_lshl_add_u64 v[66:67], v[66:67], 0, s[56:57]
	v_mov_b32_e32 v32, 0
	v_mov_b32_e32 v33, 0
	v_lshl_add_u64 v[62:63], s[64:65], 0, v[14:15]
	v_lshl_add_u64 v[64:65], s[64:65], 0, v[16:17]
	v_lshlrev_b64 v[62:63], 15, v[62:63]
	v_lshlrev_b64 v[64:65], 15, v[64:65]
	v_lshl_add_u64 v[62:63], s[54:55], 0, v[62:63]
	v_lshl_add_u64 v[64:65], s[54:55], 0, v[64:65]
	v_lshl_add_u64 v[62:63], v[62:63], 0, s[58:59]
	v_lshl_add_u64 v[64:65], v[64:65], 0, s[62:63]
	v_lshl_add_u64 v[62:63], v[62:63], 0, s[50:51]
	v_lshl_add_u64 v[64:65], v[64:65], 0, s[60:61]
	v_mov_b32_e32 v34, 0
	v_mov_b32_e32 v35, 0
	v_lshl_add_u64 v[68:69], s[64:65], 0, v[20:21]
	v_lshl_add_u64 v[70:71], s[64:65], 0, v[22:23]
	v_lshlrev_b64 v[68:69], 15, v[68:69]
	v_lshlrev_b64 v[70:71], 15, v[70:71]
	v_lshl_add_u64 v[68:69], s[54:55], 0, v[68:69]
	v_lshl_add_u64 v[70:71], s[54:55], 0, v[70:71]
	v_lshl_add_u64 v[68:69], v[68:69], 0, s[58:59]
	v_lshl_add_u64 v[70:71], v[70:71], 0, s[62:63]
	v_lshl_add_u64 v[68:69], v[68:69], 0, s[50:51]
	v_lshl_add_u64 v[70:71], v[70:71], 0, s[60:61]
	v_mov_b32_e32 v38, 0
	v_mov_b32_e32 v39, 0
	s_waitcnt vmcnt(6)
	v_lshlrev_b32_e32 v92, 16, v0
	v_and_b32_e32 v93, 0xffff0000, v0
	v_lshlrev_b32_e32 v94, 16, v1
	v_and_b32_e32 v95, 0xffff0000, v1
	v_lshlrev_b32_e32 v96, 16, v2
	v_and_b32_e32 v97, 0xffff0000, v2
	v_lshlrev_b32_e32 v98, 16, v3
	s_waitcnt vmcnt(5)
	v_cvt_pk_f32_fp8_e32 v[0:1], v54
	v_cvt_pk_f32_fp8_sdwa v[74:75], v54 src0_sel:WORD_1
	v_cvt_pk_f32_fp8_e32 v[80:81], v55
	v_cvt_pk_f32_fp8_sdwa v[54:55], v55 src0_sel:WORD_1
	s_waitcnt vmcnt(3)
	v_cvt_pk_f32_fp8_e32 v[72:73], v58
	v_cvt_pk_f32_fp8_sdwa v[78:79], v58 src0_sel:WORD_1
	v_cvt_pk_f32_fp8_e32 v[84:85], v59
	v_cvt_pk_f32_fp8_sdwa v[58:59], v59 src0_sel:WORD_1
	v_mov_b32_e32 v88, v74
	v_mov_b32_e32 v74, v80
	v_mov_b32_e32 v80, v54
	v_mov_b32_e32 v89, v78
	v_mov_b32_e32 v78, v75
	v_mov_b32_e32 v75, v84
	v_mov_b32_e32 v84, v81
	v_mov_b32_e32 v81, v58
	v_mov_b32_e32 v58, v55
	v_and_b32_e32 v99, 0xffff0000, v3
	v_cvt_pk_f32_fp8_e32 v[2:3], v56
	v_cvt_pk_f32_fp8_sdwa v[76:77], v56 src0_sel:WORD_1
	v_cvt_pk_f32_fp8_e32 v[82:83], v57
	v_cvt_pk_f32_fp8_sdwa v[56:57], v57 src0_sel:WORD_1
	v_mov_b32_e32 v86, v72
	v_mov_b32_e32 v40, 0
	v_mov_b32_e32 v41, 0
	s_add_i32 s6, s6, s8
	s_add_i32 s0, s0, s1
	s_add_i32 s3, s3, s10
	s_add_u32 s18, s18, s20
	s_addc_u32 s19, s19, s21
	s_add_u32 s24, s24, s20
	s_addc_u32 s25, s25, s21
	s_cmpk_lt_i32 s6, 0x6000
	s_waitcnt vmcnt(0)
;     __device__ __forceinline__ unsigned a(const pg8::Unit& u) const { return (unsigned)u.pm * (256u * K * 2u); }
;     __device__ __forceinline__ unsigned a(const pg8::Unit& u) const { return (unsigned)u.pm * (256u * K * 2u); }
;     __device__ __forceinline__ unsigned a(const pg8::Unit& u) const { return (unsigned)u.pm * (256u * K * 2u); }
;     __device__ __forceinline__ unsigned a(const pg8::Unit& u) const { return (unsigned)u.pm * (256u * K * 2u); }
;     __device__ __forceinline__ unsigned a(const pg8::Unit& u) const { return (unsigned)u.pm * (256u * K * 2u); }
; __device__ __forceinline__ void p3_combine(const Frame& F) {
;     ...
;             const int col = j * 512 + lane * 8, head = col >> 7; const size_t e = (size_t)m * EB + col;
;             const int sq = m >> 13, pos = m & (SEQ - 1);
;             const float l0 = F.LSE[((size_t)(0 * 16 + head) * NSEQ + sq) * SEQ + pos], l1 = F.LSE[((size_t)(1 * 16 + head) * NSEQ + sq) * SEQ + ((pos & 3) << 11) + (pos >> 2)],
;                         l2 = F.LSE[((size_t)(2 * 16 + head) * NSEQ + sq) * SEQ + ((pos & 15) << 9) + (pos >> 4)];
;             const float mx = fmaxf(l0, fmaxf(l1, l2));
;             float e0 = __builtin_amdgcn_exp2f(l0 - mx), e1 = __builtin_amdgcn_exp2f(l1 - mx), e2 = __builtin_amdgcn_exp2f(l2 - mx);
;             const float inv = 1.f / (e0 + e1 + e2); e0 *= inv; e1 *= inv; e2 *= inv;
;             const u32x2 a = *(const u32x2*)((const unsigned char*)F.OG0 + e), b = *(const u32x2*)((const unsigned char*)F.OG1 + e), c = *(const u32x2*)((const unsigned char*)F.OG2 + e);
;             const u32x4 z = *(const u32x4*)(F.ZB + e);
;             const unsigned aw[2] = {a.x, a.y}, bw[2] = {b.x, b.y}, cw[2] = {c.x, c.y}, zw[4] = {z.x, z.y, z.z, z.w};
;             float ov[8];
;     ...
;             P3_PAIR(0, 0, false); P3_PAIR(1, 0, true); P3_PAIR(2, 1, false); P3_PAIR(3, 1, true);
;     ...
;             int lo8 = 0, hi8 = 0;
;             lo8 = __builtin_amdgcn_cvt_pk_fp8_f32(ov[0], ov[1], lo8, false); lo8 = __builtin_amdgcn_cvt_pk_fp8_f32(ov[2], ov[3], lo8, true);
;             hi8 = __builtin_amdgcn_cvt_pk_fp8_f32(ov[4], ov[5], hi8, false); hi8 = __builtin_amdgcn_cvt_pk_fp8_f32(ov[6], ov[7], hi8, true);
;             *(u32x2*)(F.OBZ8 + e) = (u32x2){(unsigned)lo8, (unsigned)hi8};
	v_max3_f32 v54, v87, v90, v91
	v_sub_f32_e32 v55, v87, v54
	v_sub_f32_e32 v87, v90, v54
	v_sub_f32_e32 v90, v91, v54
	v_exp_f32_e32 v54, v55
	v_exp_f32_e32 v87, v87
	v_exp_f32_e32 v55, v90
	v_add_f32_e32 v90, v54, v87
	v_add_f32_e32 v90, v55, v90
	v_div_scale_f32 v91, s[56:57], v90, v90, 1.0
	v_rcp_f32_e32 v101, v91
	v_div_scale_f32 v100, vcc, 1.0, v90, 1.0
	v_fma_f32 v102, -v91, v101, 1.0
	v_fmac_f32_e32 v101, v102, v101
	v_mul_f32_e32 v102, v100, v101
	v_fma_f32 v103, -v91, v102, v100
	v_fmac_f32_e32 v102, v103, v101
	v_fma_f32 v91, -v91, v102, v100
	v_div_fmas_f32 v91, v91, v101, v102
	v_div_fixup_f32 v90, v91, v90, 1.0
	v_pk_mul_f32 v[54:55], v[54:55], v[90:91] op_sel_hi:[1,0]
	v_mul_f32_e32 v100, v87, v90
	v_pk_mov_b32 v[90:91], v[54:55], v[0:1] op_sel:[1,0]
	v_mov_b32_e32 v87, v54
	v_mov_b32_e32 v0, v55
	v_pk_mov_b32 v[72:73], v[72:73], v[54:55] op_sel:[1,0]
	v_pk_mul_f32 v[88:89], v[54:55], v[88:89]
	v_pk_mul_f32 v[78:79], v[54:55], v[78:79]
	v_pk_mul_f32 v[74:75], v[54:55], v[74:75]
	v_pk_mul_f32 v[84:85], v[54:55], v[84:85]
	v_pk_mul_f32 v[80:81], v[54:55], v[80:81]
	v_pk_mul_f32 v[54:55], v[54:55], v[58:59]
	v_pk_mul_f32 v[58:59], v[90:91], v[86:87]
	v_pk_mul_f32 v[0:1], v[0:1], v[72:73]
	v_fma_f32 v72, v100, v76, v88
	v_fma_f32 v73, v100, v77, v78
	v_fma_f32 v74, v100, v82, v74
	v_fma_f32 v76, v100, v83, v84
	v_fma_f32 v2, v2, v100, v59
	v_fma_f32 v1, v3, v100, v1
	v_fma_f32 v54, v100, v57, v54
	v_add_f32_e32 v3, v72, v89
	v_add_f32_e32 v57, v73, v79
	v_add_f32_e32 v59, v74, v75
	v_add_f32_e32 v72, v76, v85
	v_add_f32_e32 v2, v58, v2
	v_add_f32_e32 v0, v0, v1
	v_add_f32_e32 v54, v54, v55
	v_mul_f32_e32 v1, v3, v94
	v_mul_f32_e32 v3, v57, v95
	v_mul_f32_e32 v55, v59, v96
	v_mul_f32_e32 v57, v72, v97
	v_mul_f32_e32 v2, v2, v92
	v_mul_f32_e32 v0, v0, v93
	v_add_f32_e32 v55, v55, v55
	v_add_f32_e32 v57, v57, v57
	v_add_f32_e32 v2, v2, v2
	v_add_f32_e32 v0, v0, v0
	v_fma_f32 v56, v100, v56, v80
	v_cvt_pk_fp8_f32 v33, v55, v57
	v_cvt_pk_fp8_f32 v32, v2, v0
	v_add_f32_e32 v56, v56, v81
	v_mul_f32_e32 v56, v56, v98
	v_mul_f32_e32 v54, v54, v99
	v_add_f32_e32 v1, v1, v1
	v_add_f32_e32 v3, v3, v3
	v_add_f32_e32 v56, v56, v56
	v_add_f32_e32 v54, v54, v54
	v_cvt_pk_fp8_f32 v33, v56, v54 op_sel:[0,0,1]
	v_cvt_pk_fp8_f32 v32, v1, v3 op_sel:[0,0,1]
	global_store_dwordx2 v[36:37], v[32:33], off
	global_load_dword v80, v[60:61], off
	global_load_dword v81, v[62:63], off
	global_load_dword v82, v[64:65], off
	s_nop 0
	global_load_dwordx2 v[32:33], v[44:45], off offset:512
	global_load_dwordx2 v[54:55], v[46:47], off offset:512
	global_load_dwordx2 v[56:57], v[48:49], off offset:512
	global_load_dwordx4 v[0:3], v[30:31], off offset:-2048
	s_waitcnt vmcnt(4)
	v_max3_f32 v83, v80, v81, v82
	s_waitcnt vmcnt(3)
	v_cvt_pk_f32_fp8_e32 v[58:59], v32
	v_cvt_pk_f32_fp8_sdwa v[64:65], v32 src0_sel:WORD_1
	s_waitcnt vmcnt(1)
	v_cvt_pk_f32_fp8_e32 v[62:63], v56
	s_waitcnt vmcnt(0)
	v_lshlrev_b32_e32 v88, 16, v2
	v_and_b32_e32 v89, 0xffff0000, v2
	v_lshlrev_b32_e32 v90, 16, v3
	v_and_b32_e32 v91, 0xffff0000, v3
	v_sub_f32_e32 v2, v80, v83
	v_sub_f32_e32 v3, v81, v83
	v_lshlrev_b32_e32 v84, 16, v0
	v_and_b32_e32 v85, 0xffff0000, v0
	v_lshlrev_b32_e32 v86, 16, v1
	v_and_b32_e32 v87, 0xffff0000, v1
	v_cvt_pk_f32_fp8_e32 v[0:1], v33
	v_cvt_pk_f32_fp8_sdwa v[32:33], v33 src0_sel:WORD_1
	v_sub_f32_e32 v80, v82, v83
	v_exp_f32_e32 v2, v2
	v_exp_f32_e32 v81, v3
	v_exp_f32_e32 v3, v80
	v_cvt_pk_f32_fp8_sdwa v[74:75], v56 src0_sel:WORD_1
	v_cvt_pk_f32_fp8_e32 v[78:79], v57
	v_cvt_pk_f32_fp8_sdwa v[56:57], v57 src0_sel:WORD_1
	v_mov_b32_e32 v82, v64
	v_mov_b32_e32 v64, v0
	v_mov_b32_e32 v0, v32
	v_add_f32_e32 v32, v2, v81
	v_add_f32_e32 v32, v3, v32
	v_mov_b32_e32 v83, v74
	v_mov_b32_e32 v74, v65
	v_mov_b32_e32 v65, v78
	v_mov_b32_e32 v78, v1
	v_mov_b32_e32 v1, v56
	v_mov_b32_e32 v56, v33
	v_div_scale_f32 v33, s[56:57], v32, v32, 1.0
	v_rcp_f32_e32 v93, v33
	v_div_scale_f32 v92, vcc, 1.0, v32, 1.0
	v_cvt_pk_f32_fp8_e32 v[60:61], v54
	v_fma_f32 v94, -v33, v93, 1.0
	v_fmac_f32_e32 v93, v94, v93
	v_mul_f32_e32 v94, v92, v93
	v_fma_f32 v95, -v33, v94, v92
	v_fmac_f32_e32 v94, v95, v93
	v_fma_f32 v33, -v33, v94, v92
	v_div_fmas_f32 v33, v33, v93, v94
	v_cvt_pk_f32_fp8_sdwa v[72:73], v54 src0_sel:WORD_1
	v_cvt_pk_f32_fp8_e32 v[76:77], v55
	v_cvt_pk_f32_fp8_sdwa v[54:55], v55 src0_sel:WORD_1
	v_div_fixup_f32 v32, v33, v32, 1.0
	v_pk_mul_f32 v[2:3], v[2:3], v[32:33] op_sel_hi:[1,0]
	v_mov_b32_e32 v80, v62
	v_mul_f32_e32 v92, v81, v32
	v_pk_mov_b32 v[32:33], v[2:3], v[58:59] op_sel:[1,0]
	v_mov_b32_e32 v81, v2
	v_mov_b32_e32 v58, v3
	v_pk_mov_b32 v[62:63], v[62:63], v[2:3] op_sel:[1,0]
	v_pk_mul_f32 v[82:83], v[2:3], v[82:83]
	v_pk_mul_f32 v[74:75], v[2:3], v[74:75]
	v_pk_mul_f32 v[64:65], v[2:3], v[64:65]
	v_pk_mul_f32 v[78:79], v[2:3], v[78:79]
	v_pk_mul_f32 v[0:1], v[2:3], v[0:1]
	v_pk_mul_f32 v[2:3], v[2:3], v[56:57]
	v_pk_mul_f32 v[32:33], v[32:33], v[80:81]
	v_pk_mul_f32 v[56:57], v[58:59], v[62:63]
	v_fma_f32 v58, v92, v72, v82
	v_fma_f32 v59, v92, v73, v74
	v_fma_f32 v62, v92, v76, v64
	v_fma_f32 v63, v92, v77, v78
	v_fma_f32 v0, v92, v54, v0
	v_fma_f32 v2, v92, v55, v2
	v_fma_f32 v33, v60, v92, v33
	v_fma_f32 v54, v61, v92, v57
	v_add_f32_e32 v55, v58, v83
	v_add_f32_e32 v57, v59, v75
	v_add_f32_e32 v58, v62, v65
	v_add_f32_e32 v59, v63, v79
	v_add_f32_e32 v0, v0, v1
	v_add_f32_e32 v1, v2, v3
	v_add_f32_e32 v2, v32, v33
	v_add_f32_e32 v3, v56, v54
	v_mul_f32_e32 v32, v55, v86
	v_mul_f32_e32 v54, v58, v88
	v_mul_f32_e32 v55, v59, v89
	v_mul_f32_e32 v2, v2, v84
	v_mul_f32_e32 v3, v3, v85
	v_add_f32_e32 v54, v54, v54
	v_add_f32_e32 v55, v55, v55
	v_add_f32_e32 v2, v2, v2
	v_add_f32_e32 v3, v3, v3
	v_cvt_pk_fp8_f32 v35, v54, v55
	v_cvt_pk_fp8_f32 v34, v2, v3
	v_mul_f32_e32 v33, v57, v87
	v_mul_f32_e32 v0, v0, v90
	v_mul_f32_e32 v1, v1, v91
	v_add_f32_e32 v32, v32, v32
	v_add_f32_e32 v33, v33, v33
	v_add_f32_e32 v0, v0, v0
	v_add_f32_e32 v1, v1, v1
	v_cvt_pk_fp8_f32 v35, v0, v1 op_sel:[0,0,1]
	v_cvt_pk_fp8_f32 v34, v32, v33 op_sel:[0,0,1]
	global_store_dwordx2 v[36:37], v[34:35], off offset:512
	global_load_dword v72, v[66:67], off
	global_load_dword v73, v[68:69], off
	global_load_dword v74, v[70:71], off
	global_load_dwordx2 v[32:33], v[44:45], off offset:1024
	s_nop 0
	global_load_dwordx2 v[34:35], v[46:47], off offset:1024
	global_load_dwordx2 v[54:55], v[48:49], off offset:1024
	global_load_dwordx4 v[0:3], v[30:31], off offset:-1024
	s_waitcnt vmcnt(4)
;     __device__ __forceinline__ unsigned a(const pg8::Unit& u) const { return (unsigned)u.pm * (256u * K * 2u); }
;     __device__ __forceinline__ unsigned a(const pg8::Unit& u) const { return (unsigned)u.pm * (256u * K * 2u); }
;     __device__ __forceinline__ unsigned a(const pg8::Unit& u) const { return (unsigned)u.pm * (256u * K * 2u); }
;     __device__ __forceinline__ unsigned a(const pg8::Unit& u) const { return (unsigned)u.pm * (256u * K * 2u); }
;     __device__ __forceinline__ unsigned a(const pg8::Unit& u) const { return (unsigned)u.pm * (256u * K * 2u); }
; __device__ __forceinline__ void p3_combine(const Frame& F) {
;     ...
;             const int col = j * 512 + lane * 8, head = col >> 7; const size_t e = (size_t)m * EB + col;
;             const int sq = m >> 13, pos = m & (SEQ - 1);
;             const float l0 = F.LSE[((size_t)(0 * 16 + head) * NSEQ + sq) * SEQ + pos], l1 = F.LSE[((size_t)(1 * 16 + head) * NSEQ + sq) * SEQ + ((pos & 3) << 11) + (pos >> 2)],
;                         l2 = F.LSE[((size_t)(2 * 16 + head) * NSEQ + sq) * SEQ + ((pos & 15) << 9) + (pos >> 4)];
;             const float mx = fmaxf(l0, fmaxf(l1, l2));
;             float e0 = __builtin_amdgcn_exp2f(l0 - mx), e1 = __builtin_amdgcn_exp2f(l1 - mx), e2 = __builtin_amdgcn_exp2f(l2 - mx);
;             const float inv = 1.f / (e0 + e1 + e2); e0 *= inv; e1 *= inv; e2 *= inv;
;             const u32x2 a = *(const u32x2*)((const unsigned char*)F.OG0 + e), b = *(const u32x2*)((const unsigned char*)F.OG1 + e), c = *(const u32x2*)((const unsigned char*)F.OG2 + e);
;             const u32x4 z = *(const u32x4*)(F.ZB + e);
;             const unsigned aw[2] = {a.x, a.y}, bw[2] = {b.x, b.y}, cw[2] = {c.x, c.y}, zw[4] = {z.x, z.y, z.z, z.w};
;             float ov[8];
;     ...
;             P3_PAIR(0, 0, false); P3_PAIR(1, 0, true); P3_PAIR(2, 1, false); P3_PAIR(3, 1, true);
;     ...
;             int lo8 = 0, hi8 = 0;
;             lo8 = __builtin_amdgcn_cvt_pk_fp8_f32(ov[0], ov[1], lo8, false); lo8 = __builtin_amdgcn_cvt_pk_fp8_f32(ov[2], ov[3], lo8, true);
;             hi8 = __builtin_amdgcn_cvt_pk_fp8_f32(ov[4], ov[5], hi8, false); hi8 = __builtin_amdgcn_cvt_pk_fp8_f32(ov[6], ov[7], hi8, true);
;             *(u32x2*)(F.OBZ8 + e) = (u32x2){(unsigned)lo8, (unsigned)hi8};
	v_max3_f32 v75, v72, v73, v74
	s_waitcnt vmcnt(3)
	v_cvt_pk_f32_fp8_e32 v[56:57], v32
	v_cvt_pk_f32_fp8_sdwa v[62:63], v32 src0_sel:WORD_1
	s_waitcnt vmcnt(1)
	v_cvt_pk_f32_fp8_e32 v[60:61], v54
	s_waitcnt vmcnt(0)
	v_lshlrev_b32_e32 v80, 16, v2
	v_and_b32_e32 v81, 0xffff0000, v2
	v_lshlrev_b32_e32 v82, 16, v3
	v_and_b32_e32 v83, 0xffff0000, v3
	v_sub_f32_e32 v2, v72, v75
	v_sub_f32_e32 v3, v73, v75
	v_lshlrev_b32_e32 v76, 16, v0
	v_and_b32_e32 v77, 0xffff0000, v0
	v_lshlrev_b32_e32 v78, 16, v1
	v_and_b32_e32 v79, 0xffff0000, v1
	v_cvt_pk_f32_fp8_e32 v[0:1], v33
	v_cvt_pk_f32_fp8_sdwa v[32:33], v33 src0_sel:WORD_1
	v_sub_f32_e32 v72, v74, v75
	v_exp_f32_e32 v2, v2
	v_exp_f32_e32 v73, v3
	v_exp_f32_e32 v3, v72
	v_cvt_pk_f32_fp8_sdwa v[66:67], v54 src0_sel:WORD_1
	v_cvt_pk_f32_fp8_e32 v[70:71], v55
	v_cvt_pk_f32_fp8_sdwa v[54:55], v55 src0_sel:WORD_1
	v_mov_b32_e32 v74, v62
	v_mov_b32_e32 v62, v0
	v_mov_b32_e32 v0, v32
	v_add_f32_e32 v32, v2, v73
	v_add_f32_e32 v32, v3, v32
	v_mov_b32_e32 v75, v66
	v_mov_b32_e32 v66, v63
	v_mov_b32_e32 v63, v70
	v_mov_b32_e32 v70, v1
	v_mov_b32_e32 v1, v54
	v_mov_b32_e32 v54, v33
	v_div_scale_f32 v33, s[56:57], v32, v32, 1.0
	v_rcp_f32_e32 v85, v33
	v_div_scale_f32 v84, vcc, 1.0, v32, 1.0
	v_cvt_pk_f32_fp8_e32 v[58:59], v34
	v_fma_f32 v86, -v33, v85, 1.0
	v_fmac_f32_e32 v85, v86, v85
	v_mul_f32_e32 v86, v84, v85
	v_fma_f32 v87, -v33, v86, v84
	v_fmac_f32_e32 v86, v87, v85
	v_fma_f32 v33, -v33, v86, v84
	v_div_fmas_f32 v33, v33, v85, v86
	v_cvt_pk_f32_fp8_sdwa v[64:65], v34 src0_sel:WORD_1
	v_cvt_pk_f32_fp8_e32 v[68:69], v35
	v_cvt_pk_f32_fp8_sdwa v[34:35], v35 src0_sel:WORD_1
	v_div_fixup_f32 v32, v33, v32, 1.0
	v_pk_mul_f32 v[2:3], v[2:3], v[32:33] op_sel_hi:[1,0]
	v_mov_b32_e32 v72, v60
	v_mul_f32_e32 v84, v73, v32
	v_pk_mov_b32 v[32:33], v[2:3], v[56:57] op_sel:[1,0]
	v_mov_b32_e32 v73, v2
	v_mov_b32_e32 v56, v3
	v_pk_mov_b32 v[60:61], v[60:61], v[2:3] op_sel:[1,0]
	v_pk_mul_f32 v[74:75], v[2:3], v[74:75]
	v_pk_mul_f32 v[66:67], v[2:3], v[66:67]
	v_pk_mul_f32 v[62:63], v[2:3], v[62:63]
	v_pk_mul_f32 v[70:71], v[2:3], v[70:71]
	v_pk_mul_f32 v[0:1], v[2:3], v[0:1]
	v_pk_mul_f32 v[2:3], v[2:3], v[54:55]
	v_pk_mul_f32 v[32:33], v[32:33], v[72:73]
	v_pk_mul_f32 v[54:55], v[56:57], v[60:61]
	v_fma_f32 v56, v84, v64, v74
	v_fma_f32 v57, v84, v65, v66
	v_fma_f32 v60, v84, v68, v62
	v_fma_f32 v61, v84, v69, v70
	v_fma_f32 v0, v84, v34, v0
	v_fma_f32 v2, v84, v35, v2
	v_fma_f32 v33, v58, v84, v33
	v_fma_f32 v34, v59, v84, v55
	v_add_f32_e32 v35, v56, v75
	v_add_f32_e32 v55, v57, v67
	v_add_f32_e32 v56, v60, v63
	v_add_f32_e32 v57, v61, v71
	v_add_f32_e32 v0, v0, v1
	v_add_f32_e32 v1, v2, v3
	v_add_f32_e32 v2, v32, v33
	v_add_f32_e32 v3, v54, v34
	v_mul_f32_e32 v32, v35, v78
	v_mul_f32_e32 v34, v56, v80
	v_mul_f32_e32 v35, v57, v81
	v_mul_f32_e32 v2, v2, v76
	v_mul_f32_e32 v3, v3, v77
	v_add_f32_e32 v34, v34, v34
	v_add_f32_e32 v35, v35, v35
	v_add_f32_e32 v2, v2, v2
	v_add_f32_e32 v3, v3, v3
	v_cvt_pk_fp8_f32 v39, v34, v35
	v_cvt_pk_fp8_f32 v38, v2, v3
	v_mul_f32_e32 v33, v55, v79
	v_mul_f32_e32 v0, v0, v82
	v_mul_f32_e32 v1, v1, v83
	v_add_f32_e32 v32, v32, v32
	v_add_f32_e32 v33, v33, v33
	v_add_f32_e32 v0, v0, v0
	v_add_f32_e32 v1, v1, v1
	v_cvt_pk_fp8_f32 v39, v0, v1 op_sel:[0,0,1]
	v_cvt_pk_fp8_f32 v38, v32, v33 op_sel:[0,0,1]
	global_store_dwordx2 v[36:37], v[38:39], off offset:1024
	global_load_dword v58, v[42:43], off
	global_load_dword v59, v[50:51], off
	global_load_dword v60, v[52:53], off
	global_load_dwordx2 v[32:33], v[44:45], off offset:1536
	global_load_dwordx2 v[34:35], v[46:47], off offset:1536
	global_load_dwordx2 v[38:39], v[48:49], off offset:1536
	global_load_dwordx4 v[0:3], v[30:31], off
	v_lshl_add_u64 v[30:31], v[30:31], 0, s[22:23]
	s_waitcnt vmcnt(4)
;     __device__ __forceinline__ unsigned a(const pg8::Unit& u) const { return (unsigned)u.pm * (256u * K * 2u); }
;     __device__ __forceinline__ unsigned a(const pg8::Unit& u) const { return (unsigned)u.pm * (256u * K * 2u); }
;     __device__ __forceinline__ unsigned a(const pg8::Unit& u) const { return (unsigned)u.pm * (256u * K * 2u); }
;     __device__ __forceinline__ unsigned a(const pg8::Unit& u) const { return (unsigned)u.pm * (256u * K * 2u); }
;     __device__ __forceinline__ unsigned a(const pg8::Unit& u) const { return (unsigned)u.pm * (256u * K * 2u); }
; __device__ __forceinline__ void p3_combine(const Frame& F) {
;     ...
;             const int col = j * 512 + lane * 8, head = col >> 7; const size_t e = (size_t)m * EB + col;
;             const int sq = m >> 13, pos = m & (SEQ - 1);
;             const float l0 = F.LSE[((size_t)(0 * 16 + head) * NSEQ + sq) * SEQ + pos], l1 = F.LSE[((size_t)(1 * 16 + head) * NSEQ + sq) * SEQ + ((pos & 3) << 11) + (pos >> 2)],
;                         l2 = F.LSE[((size_t)(2 * 16 + head) * NSEQ + sq) * SEQ + ((pos & 15) << 9) + (pos >> 4)];
;             const float mx = fmaxf(l0, fmaxf(l1, l2));
;             float e0 = __builtin_amdgcn_exp2f(l0 - mx), e1 = __builtin_amdgcn_exp2f(l1 - mx), e2 = __builtin_amdgcn_exp2f(l2 - mx);
;             const float inv = 1.f / (e0 + e1 + e2); e0 *= inv; e1 *= inv; e2 *= inv;
;             const u32x2 a = *(const u32x2*)((const unsigned char*)F.OG0 + e), b = *(const u32x2*)((const unsigned char*)F.OG1 + e), c = *(const u32x2*)((const unsigned char*)F.OG2 + e);
;             const u32x4 z = *(const u32x4*)(F.ZB + e);
;             const unsigned aw[2] = {a.x, a.y}, bw[2] = {b.x, b.y}, cw[2] = {c.x, c.y}, zw[4] = {z.x, z.y, z.z, z.w};
;             float ov[8];
;     ...
;             P3_PAIR(0, 0, false); P3_PAIR(1, 0, true); P3_PAIR(2, 1, false); P3_PAIR(3, 1, true);
;     ...
;             int lo8 = 0, hi8 = 0;
;             lo8 = __builtin_amdgcn_cvt_pk_fp8_f32(ov[0], ov[1], lo8, false); lo8 = __builtin_amdgcn_cvt_pk_fp8_f32(ov[2], ov[3], lo8, true);
;             hi8 = __builtin_amdgcn_cvt_pk_fp8_f32(ov[4], ov[5], hi8, false); hi8 = __builtin_amdgcn_cvt_pk_fp8_f32(ov[6], ov[7], hi8, true);
;             *(u32x2*)(F.OBZ8 + e) = (u32x2){(unsigned)lo8, (unsigned)hi8};
	v_max3_f32 v61, v58, v59, v60
	s_waitcnt vmcnt(3)
	v_cvt_pk_f32_fp8_e32 v[42:43], v32
	v_cvt_pk_f32_fp8_sdwa v[48:49], v32 src0_sel:WORD_1
	s_waitcnt vmcnt(1)
	v_cvt_pk_f32_fp8_e32 v[46:47], v38
	s_waitcnt vmcnt(0)
	v_lshlrev_b32_e32 v66, 16, v2
	v_and_b32_e32 v67, 0xffff0000, v2
	v_lshlrev_b32_e32 v68, 16, v3
	v_and_b32_e32 v69, 0xffff0000, v3
	v_sub_f32_e32 v2, v58, v61
	v_sub_f32_e32 v3, v59, v61
	v_lshlrev_b32_e32 v62, 16, v0
	v_and_b32_e32 v63, 0xffff0000, v0
	v_lshlrev_b32_e32 v64, 16, v1
	v_and_b32_e32 v65, 0xffff0000, v1
	v_cvt_pk_f32_fp8_e32 v[0:1], v33
	v_cvt_pk_f32_fp8_sdwa v[32:33], v33 src0_sel:WORD_1
	v_sub_f32_e32 v58, v60, v61
	v_exp_f32_e32 v2, v2
	v_exp_f32_e32 v59, v3
	v_exp_f32_e32 v3, v58
	v_cvt_pk_f32_fp8_sdwa v[52:53], v38 src0_sel:WORD_1
	v_cvt_pk_f32_fp8_e32 v[56:57], v39
	v_cvt_pk_f32_fp8_sdwa v[38:39], v39 src0_sel:WORD_1
	v_mov_b32_e32 v60, v48
	v_mov_b32_e32 v48, v0
	v_mov_b32_e32 v0, v32
	v_add_f32_e32 v32, v2, v59
	v_add_f32_e32 v32, v3, v32
	v_mov_b32_e32 v61, v52
	v_mov_b32_e32 v52, v49
	v_mov_b32_e32 v49, v56
	v_mov_b32_e32 v56, v1
	v_mov_b32_e32 v1, v38
	v_mov_b32_e32 v38, v33
	v_div_scale_f32 v33, s[56:57], v32, v32, 1.0
	v_rcp_f32_e32 v71, v33
	v_div_scale_f32 v70, vcc, 1.0, v32, 1.0
	v_cvt_pk_f32_fp8_e32 v[44:45], v34
	v_fma_f32 v72, -v33, v71, 1.0
	v_fmac_f32_e32 v71, v72, v71
	v_mul_f32_e32 v72, v70, v71
	v_fma_f32 v73, -v33, v72, v70
	v_fmac_f32_e32 v72, v73, v71
	v_fma_f32 v33, -v33, v72, v70
	v_div_fmas_f32 v33, v33, v71, v72
	v_cvt_pk_f32_fp8_sdwa v[50:51], v34 src0_sel:WORD_1
	v_cvt_pk_f32_fp8_e32 v[54:55], v35
	v_cvt_pk_f32_fp8_sdwa v[34:35], v35 src0_sel:WORD_1
	v_div_fixup_f32 v32, v33, v32, 1.0
	v_pk_mul_f32 v[2:3], v[2:3], v[32:33] op_sel_hi:[1,0]
	v_mov_b32_e32 v58, v46
	v_mul_f32_e32 v70, v59, v32
	v_pk_mov_b32 v[32:33], v[2:3], v[42:43] op_sel:[1,0]
	v_mov_b32_e32 v59, v2
	v_mov_b32_e32 v42, v3
	v_pk_mov_b32 v[46:47], v[46:47], v[2:3] op_sel:[1,0]
	v_pk_mul_f32 v[60:61], v[2:3], v[60:61]
	v_pk_mul_f32 v[52:53], v[2:3], v[52:53]
	v_pk_mul_f32 v[48:49], v[2:3], v[48:49]
	v_pk_mul_f32 v[56:57], v[2:3], v[56:57]
	v_pk_mul_f32 v[0:1], v[2:3], v[0:1]
	v_pk_mul_f32 v[2:3], v[2:3], v[38:39]
	v_pk_mul_f32 v[32:33], v[32:33], v[58:59]
	v_pk_mul_f32 v[38:39], v[42:43], v[46:47]
	v_fma_f32 v42, v70, v50, v60
	v_fma_f32 v43, v70, v51, v52
	v_fma_f32 v46, v70, v54, v48
	v_fma_f32 v47, v70, v55, v56
	v_fma_f32 v0, v70, v34, v0
	v_fma_f32 v2, v70, v35, v2
	v_fma_f32 v33, v44, v70, v33
	v_fma_f32 v34, v45, v70, v39
	v_add_f32_e32 v35, v42, v61
	v_add_f32_e32 v39, v43, v53
	v_add_f32_e32 v42, v46, v49
	v_add_f32_e32 v43, v47, v57
	v_add_f32_e32 v0, v0, v1
	v_add_f32_e32 v1, v2, v3
	v_add_f32_e32 v2, v32, v33
	v_add_f32_e32 v3, v38, v34
	v_mul_f32_e32 v32, v35, v64
	v_mul_f32_e32 v34, v42, v66
	v_mul_f32_e32 v35, v43, v67
	v_mul_f32_e32 v2, v2, v62
	v_mul_f32_e32 v3, v3, v63
	v_add_f32_e32 v34, v34, v34
	v_add_f32_e32 v35, v35, v35
	v_add_f32_e32 v2, v2, v2
	v_add_f32_e32 v3, v3, v3
	v_cvt_pk_fp8_f32 v41, v34, v35
	v_cvt_pk_fp8_f32 v40, v2, v3
	v_mul_f32_e32 v33, v39, v65
	v_mul_f32_e32 v0, v0, v68
	v_mul_f32_e32 v1, v1, v69
	v_add_f32_e32 v32, v32, v32
	v_add_f32_e32 v33, v33, v33
	v_add_f32_e32 v0, v0, v0
	v_add_f32_e32 v1, v1, v1
	v_cvt_pk_fp8_f32 v41, v0, v1 op_sel:[0,0,1]
	v_cvt_pk_fp8_f32 v40, v32, v33 op_sel:[0,0,1]
	global_store_dwordx2 v[36:37], v[40:41], off offset:1536
	s_cbranch_scc1 .LBB0_365

; __device__ __forceinline__ void p6_final_ln(const Frame& F) {
;     ...
;     for (int m = gw; m < M; m += NGW) {
;         const float* xr = (m < SEQ) ? F.xp + (size_t)m * DM : F.xs + (size_t)(m - SEQ) * DM;
;         const bf16_t* orow = F.OUTB + (size_t)m * DM;
;         f32x4 z[16]; float s = 0.f;
; #pragma unroll
;         for (int j = 0; j < 8; ++j) { const int col = j * 512 + lane * 8;
;             const f32x4 xa = *(const f32x4*)(xr + col), xb = *(const f32x4*)(xr + col + 4); const u32x4 o = *(const u32x4*)(orow + col);
;             z[2 * j]     = xa * DN_ALPHA + (f32x4){bflo(o.x), bfhi(o.x), bflo(o.y), bfhi(o.y)};
;             z[2 * j + 1] = xb * DN_ALPHA + (f32x4){bflo(o.z), bfhi(o.z), bflo(o.w), bfhi(o.w)};
;             s += (z[2 * j][0] + z[2 * j][1]) + (z[2 * j][2] + z[2 * j][3]) + (z[2 * j + 1][0] + z[2 * j + 1][1]) + (z[2 * j + 1][2] + z[2 * j + 1][3]); }
.LBB0_575:
	s_barrier
	s_lshl_b64 s[18:19], s[12:13], 13
	s_add_u32 s18, s26, s18
	s_addc_u32 s19, s27, s19
	v_lshlrev_b32_e32 v70, 1, v4
	global_load_dwordx4 v[42:45], v70, s[18:19]
	global_load_dwordx4 v[46:49], v70, s[18:19] offset:1024
	global_load_dwordx4 v[50:53], v70, s[18:19] offset:2048
	v_lshlrev_b32_e32 v109, 2, v4
	global_load_dwordx4 v[54:57], v109, s[16:17]
	global_load_dwordx4 v[58:61], v109, s[16:17] offset:16
	global_load_dwordx4 v[62:65], v109, s[16:17] offset:2048
	global_load_dwordx4 v[66:69], v109, s[16:17] offset:2064
	global_load_dwordx4 v[74:77], v104, s[16:17]
	global_load_dwordx4 v[78:81], v104, s[16:17] offset:16
	global_load_dwordx4 v[0:3], v105, s[16:17] offset:16
	global_load_dwordx4 v[82:85], v105, s[16:17]
	v_lshlrev_b32_e32 v107, 2, v6
	v_lshlrev_b32_e32 v71, 1, v6
	v_lshlrev_b32_e32 v108, 2, v8
	v_lshlrev_b32_e32 v72, 1, v8
	global_load_dwordx4 v[86:89], v107, s[16:17] offset:16
	global_load_dwordx4 v[94:97], v107, s[16:17]
	global_load_dwordx4 v[112:115], v108, s[16:17] offset:16
	global_load_dwordx4 v[116:119], v108, s[16:17]
	global_load_dwordx4 v[98:101], v70, s[18:19] offset:3072
	global_load_dwordx4 v[120:123], v71, s[18:19]
	global_load_dwordx4 v[124:127], v72, s[18:19]
	s_lshl_b64 s[12:13], s[12:13], 14
	s_add_u32 s12, s38, s12
	s_addc_u32 s13, s39, s13
	s_add_u32 s0, s0, s2
	s_addc_u32 s1, s1, s3
	s_add_u32 s6, s6, s8
	s_addc_u32 s7, s7, s9
	s_cmpk_lt_i32 s0, 0x6000
	s_waitcnt vmcnt(17)
	v_lshlrev_b32_e32 v70, 16, v42
	v_and_b32_e32 v71, 0xffff0000, v42
	v_lshlrev_b32_e32 v42, 16, v43
	v_and_b32_e32 v43, 0xffff0000, v43
	v_lshlrev_b32_e32 v72, 16, v44
	v_and_b32_e32 v73, 0xffff0000, v44
	v_lshlrev_b32_e32 v44, 16, v45
	v_and_b32_e32 v45, 0xffff0000, v45
	s_waitcnt vmcnt(16)
	v_lshlrev_b32_e32 v110, 16, v46
	v_and_b32_e32 v111, 0xffff0000, v46
	v_lshlrev_b32_e32 v46, 16, v47
	v_and_b32_e32 v47, 0xffff0000, v47
	v_lshlrev_b32_e32 v128, 16, v48
	v_and_b32_e32 v129, 0xffff0000, v48
	v_lshlrev_b32_e32 v48, 16, v49
	v_and_b32_e32 v49, 0xffff0000, v49
	s_waitcnt vmcnt(14)
	v_pk_fma_f32 v[90:91], v[56:57], s[10:11], v[42:43] op_sel_hi:[1,0,1]
	v_pk_fma_f32 v[92:93], v[54:55], s[10:11], v[70:71] op_sel_hi:[1,0,1]
	s_waitcnt vmcnt(13)
	v_pk_fma_f32 v[70:71], v[60:61], s[10:11], v[44:45] op_sel_hi:[1,0,1]
	v_pk_fma_f32 v[72:73], v[58:59], s[10:11], v[72:73] op_sel_hi:[1,0,1]
	s_waitcnt vmcnt(12)
	v_pk_fma_f32 v[60:61], v[64:65], s[10:11], v[46:47] op_sel_hi:[1,0,1]
	v_pk_fma_f32 v[58:59], v[62:63], s[10:11], v[110:111] op_sel_hi:[1,0,1]
	s_waitcnt vmcnt(11)
	v_pk_fma_f32 v[56:57], v[68:69], s[10:11], v[48:49] op_sel_hi:[1,0,1]
	v_pk_fma_f32 v[54:55], v[66:67], s[10:11], v[128:129] op_sel_hi:[1,0,1]
	v_mov_b32_e32 v46, v92
	v_mov_b32_e32 v47, v58
	v_mov_b32_e32 v48, v93
	v_mov_b32_e32 v49, v59
	v_mov_b32_e32 v62, v90
	v_mov_b32_e32 v63, v60
	v_mov_b32_e32 v64, v91
	v_mov_b32_e32 v65, v61
	v_lshlrev_b32_e32 v130, 16, v50
	v_and_b32_e32 v131, 0xffff0000, v50
	v_lshlrev_b32_e32 v50, 16, v51
	v_and_b32_e32 v51, 0xffff0000, v51
	v_mov_b32_e32 v66, v72
	v_mov_b32_e32 v67, v54
	v_mov_b32_e32 v68, v73
	v_mov_b32_e32 v69, v55
	v_pk_add_f32 v[46:47], v[46:47], v[48:49]
	v_pk_add_f32 v[48:49], v[62:63], v[64:65]
	v_lshlrev_b32_e32 v132, 16, v52
	v_and_b32_e32 v133, 0xffff0000, v52
	v_lshlrev_b32_e32 v134, 16, v53
	v_and_b32_e32 v135, 0xffff0000, v53
	s_waitcnt vmcnt(10)
	v_pk_fma_f32 v[52:53], v[76:77], s[10:11], v[50:51] op_sel_hi:[1,0,1]
	v_pk_fma_f32 v[50:51], v[74:75], s[10:11], v[130:131] op_sel_hi:[1,0,1]
	v_mov_b32_e32 v74, v70
	v_mov_b32_e32 v75, v56
	v_mov_b32_e32 v76, v71
	v_mov_b32_e32 v77, v57
	v_pk_add_f32 v[62:63], v[66:67], v[68:69]
	v_pk_add_f32 v[46:47], v[46:47], v[48:49]
	v_pk_add_f32 v[64:65], v[74:75], v[76:77]
	v_pk_add_f32 v[46:47], v[62:63], v[46:47]
	s_waitcnt vmcnt(9)
	v_pk_fma_f32 v[44:45], v[80:81], s[10:11], v[134:135] op_sel_hi:[1,0,1]
	v_pk_fma_f32 v[42:43], v[78:79], s[10:11], v[132:133] op_sel_hi:[1,0,1]
	v_pk_mov_b32 v[78:79], v[50:51], v[52:53] op_sel:[1,0]
	v_mov_b32_e32 v80, v50
	v_mov_b32_e32 v81, v53
	v_pk_add_f32 v[46:47], v[64:65], v[46:47]
	v_pk_add_f32 v[66:67], v[78:79], v[80:81]
	v_add_f32_e32 v46, 0, v46
	v_mov_b32_e32 v48, v44
	v_mov_b32_e32 v49, v42
	v_mov_b32_e32 v62, v45
	v_mov_b32_e32 v63, v43
	v_add_f32_e32 v76, v46, v47
	v_pk_add_f32 v[46:47], v[66:67], v[66:67] op_sel:[0,1] op_sel_hi:[1,0]
	v_pk_add_f32 v[62:63], v[48:49], v[62:63]
	v_lshlrev_b32_e32 v111, 2, v10
	v_pk_add_f32 v[64:65], v[62:63], v[46:47] op_sel:[1,0] op_sel_hi:[0,1]
	v_lshlrev_b32_e32 v46, 1, v10
	global_load_dwordx4 v[46:49], v46, s[18:19]
	v_pk_add_f32 v[78:79], v[62:63], v[64:65]
	global_load_dwordx4 v[62:65], v111, s[16:17] offset:16
	global_load_dwordx4 v[66:69], v111, s[16:17]
	v_lshlrev_b32_e32 v77, 1, v12
	global_load_dwordx4 v[128:131], v77, s[18:19]
	v_lshlrev_b32_e32 v110, 2, v12
	global_load_dwordx4 v[132:135], v110, s[16:17] offset:16
	global_load_dwordx4 v[136:139], v110, s[16:17]
	s_waitcnt vmcnt(8)
	v_lshlrev_b32_e32 v74, 16, v98
	v_and_b32_e32 v75, 0xffff0000, v98
	v_lshlrev_b32_e32 v80, 16, v99
	v_and_b32_e32 v81, 0xffff0000, v99
	v_pk_fma_f32 v[80:81], v[84:85], s[10:11], v[80:81] op_sel_hi:[1,0,1]
	v_pk_fma_f32 v[74:75], v[82:83], s[10:11], v[74:75] op_sel_hi:[1,0,1]
	v_lshlrev_b32_e32 v82, 16, v100
	v_and_b32_e32 v83, 0xffff0000, v100
	v_lshlrev_b32_e32 v84, 16, v101
	v_and_b32_e32 v85, 0xffff0000, v101
	v_pk_fma_f32 v[100:101], v[2:3], s[10:11], v[84:85] op_sel_hi:[1,0,1]
	v_pk_fma_f32 v[98:99], v[0:1], s[10:11], v[82:83] op_sel_hi:[1,0,1]
	s_waitcnt vmcnt(7)
; __device__ __forceinline__ float wave_sum(float v) {
; #pragma unroll
;     for (int o = 1; o < 64; o <<= 1) v += __shfl_xor(v, o);
;     return v;
; __device__ __forceinline__ void p6_final_ln(const Frame& F) {
;     ...
;         for (int j = 0; j < 8; ++j) { const int col = j * 512 + lane * 8;
;             const f32x4 xa = *(const f32x4*)(xr + col), xb = *(const f32x4*)(xr + col + 4); const u32x4 o = *(const u32x4*)(orow + col);
;             z[2 * j]     = xa * DN_ALPHA + (f32x4){bflo(o.x), bfhi(o.x), bflo(o.y), bfhi(o.y)};
;             z[2 * j + 1] = xb * DN_ALPHA + (f32x4){bflo(o.z), bfhi(o.z), bflo(o.w), bfhi(o.w)};
;             s += (z[2 * j][0] + z[2 * j][1]) + (z[2 * j][2] + z[2 * j][3]) + (z[2 * j + 1][0] + z[2 * j + 1][1]) + (z[2 * j + 1][2] + z[2 * j + 1][3]); }
;         const float mean = wave_sum(s) * (1.f / DM); float q = 0.f;
	v_lshlrev_b32_e32 v82, 16, v120
	v_and_b32_e32 v83, 0xffff0000, v120
	v_lshlrev_b32_e32 v84, 16, v121
	v_and_b32_e32 v85, 0xffff0000, v121
	v_pk_fma_f32 v[96:97], v[96:97], s[10:11], v[84:85] op_sel_hi:[1,0,1]
	v_pk_fma_f32 v[94:95], v[94:95], s[10:11], v[82:83] op_sel_hi:[1,0,1]
	v_lshlrev_b32_e32 v82, 16, v122
	v_and_b32_e32 v83, 0xffff0000, v122
	v_lshlrev_b32_e32 v84, 16, v123
	v_and_b32_e32 v85, 0xffff0000, v123
	v_add_f32_e32 v0, v74, v75
	v_add_f32_e32 v2, v80, v81
	v_pk_fma_f32 v[84:85], v[88:89], s[10:11], v[84:85] op_sel_hi:[1,0,1]
	v_pk_fma_f32 v[82:83], v[86:87], s[10:11], v[82:83] op_sel_hi:[1,0,1]
	v_mov_b32_e32 v86, v98
	v_mov_b32_e32 v87, v94
	v_mov_b32_e32 v88, v99
	v_mov_b32_e32 v89, v95
	v_mov_b32_e32 v1, v96
	v_mov_b32_e32 v3, v97
	v_pk_add_f32 v[86:87], v[86:87], v[88:89]
	v_pk_add_f32 v[0:1], v[0:1], v[2:3]
	v_mov_b32_e32 v2, v100
	v_pk_add_f32 v[0:1], v[86:87], v[0:1]
	v_mov_b32_e32 v3, v82
	v_mov_b32_e32 v86, v101
	v_mov_b32_e32 v87, v83
	v_pk_add_f32 v[2:3], v[2:3], v[86:87]
	v_mov_b32_e32 v77, v84
	v_mov_b32_e32 v79, v85
	v_pk_add_f32 v[0:1], v[2:3], v[0:1]
	v_pk_add_f32 v[2:3], v[76:77], v[78:79]
	s_nop 0
	v_pk_add_f32 v[0:1], v[2:3], v[0:1]
	s_waitcnt vmcnt(6)
	v_lshlrev_b32_e32 v2, 16, v125
	v_pk_add_f32 v[120:121], v[0:1], v[0:1] op_sel:[0,1] op_sel_hi:[1,0]
	v_lshlrev_b32_e32 v0, 16, v124
	v_and_b32_e32 v1, 0xffff0000, v124
	v_and_b32_e32 v3, 0xffff0000, v125
	v_pk_fma_f32 v[88:89], v[118:119], s[10:11], v[2:3] op_sel_hi:[1,0,1]
	v_pk_fma_f32 v[86:87], v[116:117], s[10:11], v[0:1] op_sel_hi:[1,0,1]
	v_lshlrev_b32_e32 v0, 16, v126
	v_and_b32_e32 v1, 0xffff0000, v126
	v_lshlrev_b32_e32 v2, 16, v127
	v_and_b32_e32 v3, 0xffff0000, v127
	v_pk_fma_f32 v[78:79], v[114:115], s[10:11], v[2:3] op_sel_hi:[1,0,1]
	v_pk_fma_f32 v[76:77], v[112:113], s[10:11], v[0:1] op_sel_hi:[1,0,1]
	v_pk_mov_b32 v[0:1], v[86:87], v[88:89] op_sel:[1,0]
	v_mov_b32_e32 v2, v86
	v_mov_b32_e32 v3, v89
	v_pk_add_f32 v[0:1], v[0:1], v[2:3]
	v_mov_b32_e32 v2, v78
	v_mov_b32_e32 v3, v76
	v_mov_b32_e32 v112, v79
	v_mov_b32_e32 v113, v77
	v_pk_add_f32 v[0:1], v[0:1], v[0:1] op_sel:[0,1] op_sel_hi:[1,0]
	v_pk_add_f32 v[2:3], v[2:3], v[112:113]
	s_nop 0
	v_pk_add_f32 v[0:1], v[2:3], v[0:1] op_sel:[1,0] op_sel_hi:[0,1]
	v_pk_add_f32 v[112:113], v[2:3], v[0:1]
	s_waitcnt vmcnt(5)
	v_lshlrev_b32_e32 v0, 16, v46
	v_and_b32_e32 v1, 0xffff0000, v46
	v_lshlrev_b32_e32 v2, 16, v47
	v_and_b32_e32 v3, 0xffff0000, v47
	s_waitcnt vmcnt(3)
	v_pk_fma_f32 v[68:69], v[68:69], s[10:11], v[2:3] op_sel_hi:[1,0,1]
	v_pk_fma_f32 v[66:67], v[66:67], s[10:11], v[0:1] op_sel_hi:[1,0,1]
	v_lshlrev_b32_e32 v0, 16, v48
	v_and_b32_e32 v1, 0xffff0000, v48
	v_lshlrev_b32_e32 v2, 16, v49
	v_and_b32_e32 v3, 0xffff0000, v49
	v_pk_fma_f32 v[64:65], v[64:65], s[10:11], v[2:3] op_sel_hi:[1,0,1]
	v_pk_fma_f32 v[62:63], v[62:63], s[10:11], v[0:1] op_sel_hi:[1,0,1]
	s_waitcnt vmcnt(2)
	v_lshlrev_b32_e32 v2, 16, v128
	v_and_b32_e32 v3, 0xffff0000, v128
	v_lshlrev_b32_e32 v0, 16, v129
	v_and_b32_e32 v1, 0xffff0000, v129
	s_waitcnt vmcnt(0)
	v_pk_fma_f32 v[0:1], v[138:139], s[10:11], v[0:1] op_sel_hi:[1,0,1]
	v_pk_fma_f32 v[2:3], v[136:137], s[10:11], v[2:3] op_sel_hi:[1,0,1]
	v_add_f32_e32 v114, v66, v67
	v_add_f32_e32 v116, v68, v69
	v_lshlrev_b32_e32 v48, 16, v130
	v_and_b32_e32 v49, 0xffff0000, v130
	v_mov_b32_e32 v118, v62
	v_mov_b32_e32 v119, v2
	v_mov_b32_e32 v122, v63
	v_mov_b32_e32 v123, v3
	v_mov_b32_e32 v115, v0
	v_mov_b32_e32 v117, v1
	v_lshlrev_b32_e32 v46, 16, v131
	v_and_b32_e32 v47, 0xffff0000, v131
	v_pk_fma_f32 v[48:49], v[132:133], s[10:11], v[48:49] op_sel_hi:[1,0,1]
	v_pk_add_f32 v[118:119], v[118:119], v[122:123]
	v_pk_add_f32 v[114:115], v[114:115], v[116:117]
	v_pk_fma_f32 v[46:47], v[134:135], s[10:11], v[46:47] op_sel_hi:[1,0,1]
	v_pk_add_f32 v[114:115], v[118:119], v[114:115]
	v_mov_b32_e32 v116, v64
	v_mov_b32_e32 v117, v48
	v_mov_b32_e32 v118, v65
	v_mov_b32_e32 v119, v49
	v_pk_add_f32 v[116:117], v[116:117], v[118:119]
	v_mov_b32_e32 v121, v46
	v_mov_b32_e32 v113, v47
	v_pk_add_f32 v[114:115], v[116:117], v[114:115]
	v_pk_add_f32 v[112:113], v[120:121], v[112:113]
	s_nop 0
	v_pk_add_f32 v[112:113], v[112:113], v[114:115]
	s_nop 0
	v_add_f32_e32 v102, v112, v113
	ds_bpermute_b32 v112, v5, v102
	s_waitcnt lgkmcnt(0)
	v_add_f32_e32 v102, v102, v112
	ds_bpermute_b32 v112, v7, v102
	s_waitcnt lgkmcnt(0)
	v_add_f32_e32 v102, v102, v112
	ds_bpermute_b32 v112, v9, v102
	s_waitcnt lgkmcnt(0)
	v_add_f32_e32 v102, v102, v112
	ds_bpermute_b32 v112, v11, v102
	s_waitcnt lgkmcnt(0)
	v_add_f32_e32 v102, v102, v112
	ds_bpermute_b32 v112, v13, v102
	s_waitcnt lgkmcnt(0)
	v_add_f32_e32 v102, v102, v112
	ds_bpermute_b32 v112, v103, v102
	s_waitcnt lgkmcnt(0)
; __device__ __forceinline__ void p6_final_ln(const Frame& F) {
;     ...
;         const float mean = wave_sum(s) * (1.f / DM); float q = 0.f;
; #pragma unroll
;         for (int j = 0; j < 16; ++j) { const f32x4 d = z[j] - mean; z[j] = d; q += (d[0] * d[0] + d[1] * d[1]) + (d[2] * d[2] + d[3] * d[3]); }
	v_add_f32_e32 v136, v102, v112
	v_fmamk_f32 v93, v136, 0xb9800000, v93
	v_fmac_f32_e32 v92, 0xb9800000, v136
	v_fmamk_f32 v91, v136, 0xb9800000, v91
	v_fmac_f32_e32 v90, 0xb9800000, v136
	v_pk_mul_f32 v[112:113], v[90:91], v[90:91]
	v_pk_mul_f32 v[114:115], v[92:93], v[92:93]
	v_fmamk_f32 v73, v136, 0xb9800000, v73
	v_pk_mov_b32 v[116:117], v[114:115], v[112:113] op_sel:[1,0]
	v_mov_b32_e32 v115, v113
	v_fmac_f32_e32 v72, 0xb9800000, v136
	v_fmamk_f32 v71, v136, 0xb9800000, v71
	v_fmac_f32_e32 v70, 0xb9800000, v136
	v_pk_add_f32 v[112:113], v[116:117], v[114:115]
	v_pk_mul_f32 v[114:115], v[70:71], v[70:71]
	v_pk_mul_f32 v[116:117], v[72:73], v[72:73]
	v_fmac_f32_e32 v58, 0xb9800000, v136
	v_pk_mov_b32 v[118:119], v[116:117], v[114:115] op_sel:[1,0]
	v_mov_b32_e32 v117, v115
	v_fmamk_f32 v59, v136, 0xb9800000, v59
	v_fmac_f32_e32 v60, 0xb9800000, v136
	v_mul_f32_e32 v102, v58, v58
	v_pk_add_f32 v[114:115], v[118:119], v[116:117]
	v_fmamk_f32 v61, v136, 0xb9800000, v61
	v_pk_fma_f32 v[116:117], v[58:59], v[58:59], v[102:103] op_sel_hi:[1,1,0]
	v_mul_f32_e32 v102, v60, v60
	v_pk_add_f32 v[112:113], v[112:113], v[112:113] op_sel_hi:[0,1]
	v_pk_add_f32 v[114:115], v[114:115], v[114:115] op_sel_hi:[0,1]
	v_pk_fma_f32 v[118:119], v[60:61], v[60:61], v[102:103] op_sel_hi:[1,1,0]
	v_fmamk_f32 v57, v136, 0xb9800000, v57
	v_fmac_f32_e32 v56, 0xb9800000, v136
	v_fmamk_f32 v55, v136, 0xb9800000, v55
	v_fmac_f32_e32 v54, 0xb9800000, v136
	v_mul_f32_e32 v116, v54, v54
	v_mul_f32_e32 v118, v55, v55
	v_mul_f32_e32 v112, v56, v56
	v_mul_f32_e32 v114, v57, v57
	v_pk_add_f32 v[116:117], v[116:117], v[118:119]
	v_pk_add_f32 v[112:113], v[112:113], v[114:115]
	v_fmamk_f32 v51, v136, 0xb9800000, v51
	v_fmac_f32_e32 v50, 0xb9800000, v136
	v_fmamk_f32 v53, v136, 0xb9800000, v53
	v_fmac_f32_e32 v52, 0xb9800000, v136
	v_pk_add_f32 v[112:113], v[116:117], v[112:113]
	v_pk_mul_f32 v[114:115], v[52:53], v[52:53]
	v_pk_mul_f32 v[116:117], v[50:51], v[50:51]
	v_fmac_f32_e32 v42, 0xb9800000, v136
	v_pk_mov_b32 v[118:119], v[116:117], v[114:115] op_sel:[1,0]
	v_mov_b32_e32 v117, v115
	v_fmamk_f32 v43, v136, 0xb9800000, v43
	v_fmac_f32_e32 v44, 0xb9800000, v136
	v_mul_f32_e32 v102, v42, v42
	v_pk_add_f32 v[114:115], v[118:119], v[116:117]
	v_fmamk_f32 v45, v136, 0xb9800000, v45
	v_pk_fma_f32 v[116:117], v[42:43], v[42:43], v[102:103] op_sel_hi:[1,1,0]
	v_mul_f32_e32 v102, v44, v44
	v_pk_add_f32 v[112:113], v[112:113], v[112:113] op_sel_hi:[0,1]
	v_pk_add_f32 v[114:115], v[114:115], v[114:115] op_sel_hi:[0,1]
	v_pk_fma_f32 v[118:119], v[44:45], v[44:45], v[102:103] op_sel_hi:[1,1,0]
	v_fmamk_f32 v81, v136, 0xb9800000, v81
	v_fmac_f32_e32 v80, 0xb9800000, v136
	v_fmamk_f32 v75, v136, 0xb9800000, v75
	v_fmac_f32_e32 v74, 0xb9800000, v136
	v_mul_f32_e32 v116, v74, v74
	v_mul_f32_e32 v118, v75, v75
	v_mul_f32_e32 v114, v80, v80
	v_mul_f32_e32 v112, v81, v81
	v_pk_add_f32 v[116:117], v[116:117], v[118:119]
	v_pk_add_f32 v[112:113], v[114:115], v[112:113]
	v_fmamk_f32 v99, v136, 0xb9800000, v99
	v_fmac_f32_e32 v98, 0xb9800000, v136
	v_fmamk_f32 v101, v136, 0xb9800000, v101
	v_fmac_f32_e32 v100, 0xb9800000, v136
	v_pk_add_f32 v[112:113], v[116:117], v[112:113]
	v_pk_mul_f32 v[114:115], v[100:101], v[100:101]
	v_pk_mul_f32 v[116:117], v[98:99], v[98:99]
	v_fmac_f32_e32 v94, 0xb9800000, v136
	v_pk_mov_b32 v[118:119], v[116:117], v[114:115] op_sel:[1,0]
	v_mov_b32_e32 v117, v115
	v_fmamk_f32 v95, v136, 0xb9800000, v95
	v_fmac_f32_e32 v96, 0xb9800000, v136
	v_mul_f32_e32 v102, v94, v94
	v_pk_add_f32 v[114:115], v[118:119], v[116:117]
	v_fmamk_f32 v97, v136, 0xb9800000, v97
	v_pk_fma_f32 v[116:117], v[94:95], v[94:95], v[102:103] op_sel_hi:[1,1,0]
	v_mul_f32_e32 v102, v96, v96
	v_pk_add_f32 v[112:113], v[112:113], v[112:113] op_sel_hi:[0,1]
	v_pk_add_f32 v[114:115], v[114:115], v[114:115] op_sel_hi:[0,1]
	v_pk_fma_f32 v[118:119], v[96:97], v[96:97], v[102:103] op_sel_hi:[1,1,0]
	v_fmamk_f32 v85, v136, 0xb9800000, v85
	v_fmac_f32_e32 v84, 0xb9800000, v136
	v_fmamk_f32 v83, v136, 0xb9800000, v83
	v_fmac_f32_e32 v82, 0xb9800000, v136
	v_mul_f32_e32 v116, v82, v82
	v_mul_f32_e32 v118, v83, v83
	v_mul_f32_e32 v114, v84, v84
	v_mul_f32_e32 v112, v85, v85
	v_pk_add_f32 v[116:117], v[116:117], v[118:119]
	v_pk_add_f32 v[112:113], v[114:115], v[112:113]
	v_fmamk_f32 v87, v136, 0xb9800000, v87
	v_pk_add_f32 v[112:113], v[116:117], v[112:113]
	v_fmac_f32_e32 v86, 0xb9800000, v136
	v_fmamk_f32 v89, v136, 0xb9800000, v89
	v_fmac_f32_e32 v88, 0xb9800000, v136
	v_pk_add_f32 v[128:129], v[112:113], v[112:113] op_sel_hi:[0,1]
	v_pk_mul_f32 v[112:113], v[88:89], v[88:89]
	v_pk_mul_f32 v[114:115], v[86:87], v[86:87]
	v_fmac_f32_e32 v76, 0xb9800000, v136
	v_pk_mov_b32 v[116:117], v[114:115], v[112:113] op_sel:[1,0]
	v_mov_b32_e32 v115, v113
	v_pk_add_f32 v[112:113], v[116:117], v[114:115]
	v_fmamk_f32 v77, v136, 0xb9800000, v77
	v_pk_add_f32 v[130:131], v[112:113], v[112:113] op_sel_hi:[0,1]
	global_load_dwordx4 v[112:115], v[14:15], off offset:16
	global_load_dwordx4 v[116:119], v[14:15], off
	global_load_dwordx4 v[120:123], v[16:17], off offset:16
	global_load_dwordx4 v[124:127], v[16:17], off
	v_fmac_f32_e32 v78, 0xb9800000, v136
	v_mul_f32_e32 v102, v76, v76
	v_fmamk_f32 v79, v136, 0xb9800000, v79
	v_pk_fma_f32 v[132:133], v[76:77], v[76:77], v[102:103] op_sel_hi:[1,1,0]
	v_mul_f32_e32 v102, v78, v78
	v_pk_fma_f32 v[134:135], v[78:79], v[78:79], v[102:103] op_sel_hi:[1,1,0]
	v_fmamk_f32 v69, v136, 0xb9800000, v69
	v_fmac_f32_e32 v68, 0xb9800000, v136
	v_fmamk_f32 v67, v136, 0xb9800000, v67
	v_fmac_f32_e32 v66, 0xb9800000, v136
	v_mul_f32_e32 v132, v66, v66
	v_mul_f32_e32 v134, v67, v67
; __device__ __forceinline__ float wave_sum(float v) {
; #pragma unroll
;     for (int o = 1; o < 64; o <<= 1) v += __shfl_xor(v, o);
;     return v;
; __device__ __forceinline__ void p6_final_ln(const Frame& F) {
;     ...
;         for (int j = 0; j < 16; ++j) { const f32x4 d = z[j] - mean; z[j] = d; q += (d[0] * d[0] + d[1] * d[1]) + (d[2] * d[2] + d[3] * d[3]); }
;         const float rstd = __builtin_amdgcn_rsqf(wave_sum(q) * (1.f / DM) + LN_EPS);
;         float* yr = F.out + (size_t)m * DM;
; #pragma unroll
;         for (int j = 0; j < 8; ++j) { const int col = j * 512 + lane * 8;
;             const f32x4 ga = *(const f32x4*)(F.ln_g + col), gb = *(const f32x4*)(F.ln_g + col + 4), ba = *(const f32x4*)(F.ln_b + col), bb = *(const f32x4*)(F.ln_b + col + 4);
;             *(f32x4*)(yr + col) = z[2 * j] * rstd * ga + ba; *(f32x4*)(yr + col + 4) = z[2 * j + 1] * rstd * gb + bb; }
	v_mul_f32_e32 v130, v68, v68
	v_mul_f32_e32 v128, v69, v69
	v_pk_add_f32 v[132:133], v[132:133], v[134:135]
	v_pk_add_f32 v[128:129], v[130:131], v[128:129]
	v_fmamk_f32 v63, v136, 0xb9800000, v63
	v_fmac_f32_e32 v62, 0xb9800000, v136
	v_fmamk_f32 v65, v136, 0xb9800000, v65
	v_fmac_f32_e32 v64, 0xb9800000, v136
	v_pk_add_f32 v[128:129], v[132:133], v[128:129]
	v_pk_mul_f32 v[130:131], v[64:65], v[64:65]
	v_pk_mul_f32 v[132:133], v[62:63], v[62:63]
	v_fmac_f32_e32 v2, 0xb9800000, v136
	v_pk_mov_b32 v[134:135], v[132:133], v[130:131] op_sel:[1,0]
	v_mov_b32_e32 v133, v131
	v_fmamk_f32 v3, v136, 0xb9800000, v3
	v_fmac_f32_e32 v0, 0xb9800000, v136
	v_mul_f32_e32 v102, v2, v2
	v_pk_add_f32 v[130:131], v[134:135], v[132:133]
	v_fmamk_f32 v1, v136, 0xb9800000, v1
	v_pk_fma_f32 v[132:133], v[2:3], v[2:3], v[102:103] op_sel_hi:[1,1,0]
	v_mul_f32_e32 v102, v0, v0
	v_pk_add_f32 v[128:129], v[128:129], v[128:129] op_sel_hi:[0,1]
	v_pk_add_f32 v[130:131], v[130:131], v[130:131] op_sel_hi:[0,1]
	v_pk_fma_f32 v[134:135], v[0:1], v[0:1], v[102:103] op_sel_hi:[1,1,0]
	v_fmamk_f32 v47, v136, 0xb9800000, v47
	v_fmac_f32_e32 v46, 0xb9800000, v136
	v_fmamk_f32 v49, v136, 0xb9800000, v49
	v_fmac_f32_e32 v48, 0xb9800000, v136
	v_mul_f32_e32 v132, v48, v48
	v_mul_f32_e32 v134, v49, v49
	v_mul_f32_e32 v130, v46, v46
	v_mul_f32_e32 v128, v47, v47
	v_pk_add_f32 v[132:133], v[132:133], v[134:135]
	v_pk_add_f32 v[128:129], v[130:131], v[128:129]
	s_nop 0
	v_pk_add_f32 v[128:129], v[132:133], v[128:129]
	s_nop 0
	v_add_f32_e32 v102, v128, v129
	ds_bpermute_b32 v128, v5, v102
	s_waitcnt lgkmcnt(0)
	v_add_f32_e32 v102, v102, v128
	ds_bpermute_b32 v128, v7, v102
	s_waitcnt lgkmcnt(0)
	v_add_f32_e32 v102, v102, v128
	ds_bpermute_b32 v128, v9, v102
	s_waitcnt lgkmcnt(0)
	v_add_f32_e32 v102, v102, v128
	ds_bpermute_b32 v128, v11, v102
	s_waitcnt lgkmcnt(0)
	v_add_f32_e32 v102, v102, v128
	ds_bpermute_b32 v128, v13, v102
	s_waitcnt lgkmcnt(0)
	v_add_f32_e32 v102, v102, v128
	ds_bpermute_b32 v128, v103, v102
	s_waitcnt lgkmcnt(0)
	v_add_f32_e32 v102, v102, v128
	v_fmamk_f32 v102, v102, 0x39800000, v106
	v_rsq_f32_e32 v102, v102
	s_nop 0
	v_pk_mul_f32 v[128:129], v[92:93], v[102:103] op_sel_hi:[1,0]
	v_pk_mul_f32 v[90:91], v[90:91], v[102:103] op_sel_hi:[1,0]
	v_pk_mul_f32 v[70:71], v[70:71], v[102:103] op_sel_hi:[1,0]
	s_waitcnt vmcnt(0)
	v_pk_fma_f32 v[92:93], v[118:119], v[90:91], v[126:127]
	v_pk_fma_f32 v[90:91], v[116:117], v[128:129], v[124:125]
	global_store_dwordx4 v109, v[90:93], s[12:13]
	v_pk_mul_f32 v[60:61], v[60:61], v[102:103] op_sel_hi:[1,0]
	v_pk_mul_f32 v[58:59], v[58:59], v[102:103] op_sel_hi:[1,0]
	v_pk_mul_f32 v[90:91], v[72:73], v[102:103] op_sel_hi:[1,0]
	v_pk_fma_f32 v[72:73], v[114:115], v[70:71], v[122:123]
	v_pk_fma_f32 v[70:71], v[112:113], v[90:91], v[120:121]
	global_store_dwordx4 v109, v[70:73], s[12:13] offset:16
	global_load_dwordx4 v[70:73], v[16:17], off offset:2048
	s_nop 0
	global_load_dwordx4 v[90:93], v[14:15], off offset:2048
	global_load_dwordx4 v[112:115], v[14:15], off offset:2064
	global_load_dwordx4 v[116:119], v[16:17], off offset:2064
	v_pk_mul_f32 v[56:57], v[56:57], v[102:103] op_sel_hi:[1,0]
	v_pk_mul_f32 v[54:55], v[54:55], v[102:103] op_sel_hi:[1,0]
	v_pk_mul_f32 v[52:53], v[52:53], v[102:103] op_sel_hi:[1,0]
	v_pk_mul_f32 v[50:51], v[50:51], v[102:103] op_sel_hi:[1,0]
	v_pk_mul_f32 v[44:45], v[44:45], v[102:103] op_sel_hi:[1,0]
	v_pk_mul_f32 v[42:43], v[42:43], v[102:103] op_sel_hi:[1,0]
	v_pk_mul_f32 v[76:77], v[76:77], v[102:103] op_sel_hi:[1,0]
	v_pk_mul_f32 v[68:69], v[68:69], v[102:103] op_sel_hi:[1,0]
	v_pk_mul_f32 v[66:67], v[66:67], v[102:103] op_sel_hi:[1,0]
	v_pk_mul_f32 v[64:65], v[64:65], v[102:103] op_sel_hi:[1,0]
	v_pk_mul_f32 v[62:63], v[62:63], v[102:103] op_sel_hi:[1,0]
	v_pk_mul_f32 v[46:47], v[46:47], v[102:103] op_sel_hi:[1,0]
	v_pk_mul_f32 v[48:49], v[48:49], v[102:103] op_sel_hi:[1,0]
	s_waitcnt vmcnt(2)
	v_pk_fma_f32 v[58:59], v[90:91], v[58:59], v[70:71]
	v_pk_fma_f32 v[60:61], v[92:93], v[60:61], v[72:73]
	s_waitcnt vmcnt(0)
; __device__ __forceinline__ void p6_final_ln(const Frame& F) {
;     ...
;         float* yr = F.out + (size_t)m * DM;
; #pragma unroll
;         for (int j = 0; j < 8; ++j) { const int col = j * 512 + lane * 8;
;             const f32x4 ga = *(const f32x4*)(F.ln_g + col), gb = *(const f32x4*)(F.ln_g + col + 4), ba = *(const f32x4*)(F.ln_b + col), bb = *(const f32x4*)(F.ln_b + col + 4);
;             *(f32x4*)(yr + col) = z[2 * j] * rstd * ga + ba; *(f32x4*)(yr + col + 4) = z[2 * j + 1] * rstd * gb + bb; }
	v_pk_fma_f32 v[54:55], v[112:113], v[54:55], v[116:117]
	v_pk_fma_f32 v[56:57], v[114:115], v[56:57], v[118:119]
	global_store_dwordx4 v109, v[58:61], s[12:13] offset:2048
	global_store_dwordx4 v109, v[54:57], s[12:13] offset:2064
	global_load_dwordx4 v[54:57], v[20:21], off
	s_nop 0
	global_load_dwordx4 v[58:61], v[18:19], off
	global_load_dwordx4 v[70:73], v[18:19], off offset:16
	global_load_dwordx4 v[90:93], v[20:21], off offset:16
	s_waitcnt vmcnt(2)
	v_pk_fma_f32 v[50:51], v[58:59], v[50:51], v[54:55]
	v_pk_fma_f32 v[52:53], v[60:61], v[52:53], v[56:57]
	s_waitcnt vmcnt(0)
	v_pk_fma_f32 v[42:43], v[70:71], v[42:43], v[90:91]
	v_pk_fma_f32 v[44:45], v[72:73], v[44:45], v[92:93]
	global_store_dwordx4 v104, v[50:53], s[12:13]
	global_store_dwordx4 v104, v[42:45], s[12:13] offset:16
	global_load_dwordx4 v[42:45], v[24:25], off
	s_nop 0
	global_load_dwordx4 v[50:53], v[22:23], off
	global_load_dwordx4 v[54:57], v[22:23], off offset:16
	global_load_dwordx4 v[58:61], v[24:25], off offset:16
	v_pk_mul_f32 v[70:71], v[80:81], v[102:103] op_sel_hi:[1,0]
	v_pk_mul_f32 v[72:73], v[74:75], v[102:103] op_sel_hi:[1,0]
	v_pk_mul_f32 v[74:75], v[84:85], v[102:103] op_sel_hi:[1,0]
	v_pk_mul_f32 v[80:81], v[82:83], v[102:103] op_sel_hi:[1,0]
	s_waitcnt vmcnt(2)
	v_pk_fma_f32 v[42:43], v[50:51], v[72:73], v[42:43]
	v_pk_fma_f32 v[44:45], v[52:53], v[70:71], v[44:45]
	global_store_dwordx4 v105, v[42:45], s[12:13]
	v_pk_mul_f32 v[70:71], v[96:97], v[102:103] op_sel_hi:[1,0]
	v_pk_mul_f32 v[72:73], v[94:95], v[102:103] op_sel_hi:[1,0]
	v_pk_mul_f32 v[44:45], v[100:101], v[102:103] op_sel_hi:[1,0]
	v_pk_mul_f32 v[42:43], v[98:99], v[102:103] op_sel_hi:[1,0]
	s_waitcnt vmcnt(1)
	v_pk_fma_f32 v[44:45], v[56:57], v[44:45], v[60:61]
	v_pk_fma_f32 v[42:43], v[54:55], v[42:43], v[58:59]
	global_store_dwordx4 v105, v[42:45], s[12:13] offset:16
	global_load_dwordx4 v[42:45], v[28:29], off
	s_nop 0
	global_load_dwordx4 v[50:53], v[26:27], off
	global_load_dwordx4 v[54:57], v[26:27], off offset:16
	global_load_dwordx4 v[58:61], v[28:29], off offset:16
	s_waitcnt vmcnt(2)
	v_pk_fma_f32 v[42:43], v[50:51], v[72:73], v[42:43]
	v_pk_fma_f32 v[44:45], v[52:53], v[70:71], v[44:45]
	s_waitcnt vmcnt(0)
	v_pk_fma_f32 v[50:51], v[54:55], v[80:81], v[58:59]
	v_pk_fma_f32 v[52:53], v[56:57], v[74:75], v[60:61]
	global_store_dwordx4 v107, v[42:45], s[12:13]
	global_store_dwordx4 v107, v[50:53], s[12:13] offset:16
	global_load_dwordx4 v[42:45], v[32:33], off
	s_nop 0
	global_load_dwordx4 v[50:53], v[30:31], off
	global_load_dwordx4 v[54:57], v[30:31], off offset:16
	global_load_dwordx4 v[58:61], v[32:33], off offset:16
	v_pk_mul_f32 v[70:71], v[88:89], v[102:103] op_sel_hi:[1,0]
	v_pk_mul_f32 v[72:73], v[86:87], v[102:103] op_sel_hi:[1,0]
	v_pk_mul_f32 v[74:75], v[78:79], v[102:103] op_sel_hi:[1,0]
	s_waitcnt vmcnt(2)
	v_pk_fma_f32 v[42:43], v[50:51], v[72:73], v[42:43]
	v_pk_fma_f32 v[44:45], v[52:53], v[70:71], v[44:45]
	s_waitcnt vmcnt(0)
	v_pk_fma_f32 v[50:51], v[54:55], v[76:77], v[58:59]
	v_pk_fma_f32 v[52:53], v[56:57], v[74:75], v[60:61]
	global_store_dwordx4 v108, v[42:45], s[12:13]
	global_store_dwordx4 v108, v[50:53], s[12:13] offset:16
	global_load_dwordx4 v[42:45], v[36:37], off
	s_nop 0
	global_load_dwordx4 v[50:53], v[34:35], off
	global_load_dwordx4 v[54:57], v[34:35], off offset:16
	global_load_dwordx4 v[58:61], v[36:37], off offset:16
	s_waitcnt vmcnt(2)
	v_pk_fma_f32 v[42:43], v[50:51], v[66:67], v[42:43]
	v_pk_fma_f32 v[44:45], v[52:53], v[68:69], v[44:45]
	s_waitcnt vmcnt(0)
	v_pk_fma_f32 v[50:51], v[54:55], v[62:63], v[58:59]
	v_pk_fma_f32 v[52:53], v[56:57], v[64:65], v[60:61]
	global_store_dwordx4 v111, v[42:45], s[12:13]
	global_store_dwordx4 v111, v[50:53], s[12:13] offset:16
	global_load_dwordx4 v[42:45], v[40:41], off
	s_nop 0
	global_load_dwordx4 v[50:53], v[38:39], off
	global_load_dwordx4 v[54:57], v[38:39], off offset:16
	global_load_dwordx4 v[58:61], v[40:41], off offset:16
	v_pk_mul_f32 v[62:63], v[0:1], v[102:103] op_sel_hi:[1,0]
	v_pk_mul_f32 v[0:1], v[2:3], v[102:103] op_sel_hi:[1,0]
	s_waitcnt vmcnt(2)
	v_pk_fma_f32 v[2:3], v[52:53], v[62:63], v[44:45]
	v_pk_fma_f32 v[0:1], v[50:51], v[0:1], v[42:43]
	s_waitcnt vmcnt(0)
	v_pk_fma_f32 v[42:43], v[48:49], v[54:55], v[58:59]
	v_pk_fma_f32 v[44:45], v[46:47], v[56:57], v[60:61]
	global_store_dwordx4 v110, v[0:3], s[12:13]
	global_store_dwordx4 v110, v[42:45], s[12:13] offset:16
	s_cbranch_scc0 .LBB0_578
